# w_in q/k epilogue: sum-of-squares chains interleaved across the 8 rows (no dependent packed-op chains)
# baseline (speedup 1.0000x reference)
.LBB0_465:
	s_cmp_eq_u32 s44, 2
	s_cselect_b64 s[8:9], -1, 0
	s_and_b64 s[10:11], s[8:9], s[18:19]
	s_mov_b64 s[58:59], -1
	s_andn2_b64 vcc, exec, s[10:11]
	v_cmp_gt_i32_e64 s[10:11], s81, v204
	s_cbranch_vccz .LBB0_483
	s_load_dwordx4 s[20:23], s[0:1], 0x38
	s_and_b64 s[14:15], s[8:9], exec
	v_readlane_b32 s48, v255, 40
	v_readlane_b32 s49, v255, 41
	v_lshlrev_b32_e32 v0, 2, v247
	s_waitcnt lgkmcnt(0)
	s_cselect_b32 s14, s22, s20
	s_cselect_b32 s13, s23, s21
	s_add_u32 s14, s14, s48
	s_addc_u32 s15, s13, s49
	global_load_dwordx4 v[142:145], v0, s[14:15]
	global_load_dwordx4 v[138:141], v0, s[14:15] offset:16
	global_load_dwordx4 v[134:137], v0, s[14:15] offset:128
	global_load_dwordx4 v[130:133], v0, s[14:15] offset:144
	v_readlane_b32 s22, v255, 57
	v_readlane_b32 s23, v255, 58
	v_and_b32_e32 v235, 0xfcf, v204
	v_lshlrev_b32_e32 v235, 7, v235
	v_add_u32_e32 v235, v235, v0
	v_add_u32_e32 v234, 0x1000, v235
	s_and_b64 s[14:15], s[8:9], exec
	s_cselect_b32 s21, 1.0, 0x3e38aa3b
	s_cmpk_lt_i32 s3, 0x4000
	s_cselect_b32 s20, 1, 0
	global_load_dwordx4 v[146:149], v235, s[78:79] offset:0
	global_load_dwordx4 v[150:153], v235, s[78:79] offset:16
	global_load_dwordx4 v[154:157], v235, s[22:23] offset:0
	global_load_dwordx4 v[158:161], v235, s[22:23] offset:16
	global_load_dwordx4 v[162:165], v235, s[78:79] offset:2048
	global_load_dwordx4 v[166:169], v235, s[78:79] offset:2064
	global_load_dwordx4 v[170:173], v235, s[22:23] offset:2048
	global_load_dwordx4 v[174:177], v235, s[22:23] offset:2064
	s_lshl_b32 s13, s44, 8
	v_readlane_b32 s14, v255, 52
	s_or_b32 s14, s13, s14
	s_ashr_i32 s15, s14, 31
	s_lshl_b64 s[14:15], s[14:15], 1
	s_add_u32 s27, s77, s14
	v_readlane_b32 s13, v255, 56
	s_addc_u32 s29, s13, s15
	s_add_i32 s13, s3, 0xffffc000
	s_lshr_b32 s14, s13, 8
	s_ashr_i32 s13, s3, 12
	s_mul_i32 s15, s13, 0x1100
	s_mulk_i32 s14, 0x1100
	s_addk_i32 s15, 0x100
	v_and_b32_e32 v0, 0xfcf, v204
	v_and_b32_e32 v237, 0xcf, v204
	v_add_u32_e32 v0, s15, v0
	v_or_b32_e32 v237, s14, v237
	v_cndmask_b32_e64 v0, v237, v0, s[10:11]
	v_cndmask_b32_e64 v236, v204, v0, s[8:9]
	s_and_b64 s[48:49], s[8:9], exec
	s_cselect_b32 s13, 8, 10
	s_cselect_b32 s49, s93, s29
	s_cselect_b32 s48, s85, s27
	v_lshlrev_b32_e32 v236, s13, v236
	v_lshl_add_u32 v236, v247, 1, v236
	v_pk_mul_f32 v[206:207], v[126:127], v[126:127]
	v_pk_mul_f32 v[208:209], v[110:111], v[110:111]
	v_pk_mul_f32 v[210:211], v[94:95], v[94:95]
	v_pk_mul_f32 v[212:213], v[78:79], v[78:79]
	v_pk_mul_f32 v[214:215], v[62:63], v[62:63]
	v_pk_mul_f32 v[216:217], v[46:47], v[46:47]
	v_pk_mul_f32 v[218:219], v[30:31], v[30:31]
	v_pk_mul_f32 v[220:221], v[14:15], v[14:15]
	v_pk_fma_f32 v[206:207], v[128:129], v[128:129], v[206:207]
	v_pk_fma_f32 v[208:209], v[112:113], v[112:113], v[208:209]
	v_pk_fma_f32 v[210:211], v[96:97], v[96:97], v[210:211]
	v_pk_fma_f32 v[212:213], v[80:81], v[80:81], v[212:213]
	v_pk_fma_f32 v[214:215], v[64:65], v[64:65], v[214:215]
	v_pk_fma_f32 v[216:217], v[48:49], v[48:49], v[216:217]
	v_pk_fma_f32 v[218:219], v[32:33], v[32:33], v[218:219]
	v_pk_fma_f32 v[220:221], v[16:17], v[16:17], v[220:221]
	v_pk_fma_f32 v[206:207], v[122:123], v[122:123], v[206:207]
	v_pk_fma_f32 v[208:209], v[106:107], v[106:107], v[208:209]
	v_pk_fma_f32 v[210:211], v[90:91], v[90:91], v[210:211]
	v_pk_fma_f32 v[212:213], v[74:75], v[74:75], v[212:213]
	v_pk_fma_f32 v[214:215], v[58:59], v[58:59], v[214:215]
	v_pk_fma_f32 v[216:217], v[42:43], v[42:43], v[216:217]
	v_pk_fma_f32 v[218:219], v[26:27], v[26:27], v[218:219]
	v_pk_fma_f32 v[220:221], v[10:11], v[10:11], v[220:221]
	v_pk_fma_f32 v[206:207], v[124:125], v[124:125], v[206:207]
	v_pk_fma_f32 v[208:209], v[108:109], v[108:109], v[208:209]
	v_pk_fma_f32 v[210:211], v[92:93], v[92:93], v[210:211]
	v_pk_fma_f32 v[212:213], v[76:77], v[76:77], v[212:213]
	v_pk_fma_f32 v[214:215], v[60:61], v[60:61], v[214:215]
	v_pk_fma_f32 v[216:217], v[44:45], v[44:45], v[216:217]
	v_pk_fma_f32 v[218:219], v[28:29], v[28:29], v[218:219]
	v_pk_fma_f32 v[220:221], v[12:13], v[12:13], v[220:221]
	v_pk_fma_f32 v[206:207], v[118:119], v[118:119], v[206:207]
	v_pk_fma_f32 v[208:209], v[102:103], v[102:103], v[208:209]
	v_pk_fma_f32 v[210:211], v[86:87], v[86:87], v[210:211]
	v_pk_fma_f32 v[212:213], v[70:71], v[70:71], v[212:213]
	v_pk_fma_f32 v[214:215], v[54:55], v[54:55], v[214:215]
	v_pk_fma_f32 v[216:217], v[38:39], v[38:39], v[216:217]
	v_pk_fma_f32 v[218:219], v[22:23], v[22:23], v[218:219]
	v_pk_fma_f32 v[220:221], v[6:7], v[6:7], v[220:221]
	v_pk_fma_f32 v[206:207], v[120:121], v[120:121], v[206:207]
	v_pk_fma_f32 v[208:209], v[104:105], v[104:105], v[208:209]
	v_pk_fma_f32 v[210:211], v[88:89], v[88:89], v[210:211]
	v_pk_fma_f32 v[212:213], v[72:73], v[72:73], v[212:213]
	v_pk_fma_f32 v[214:215], v[56:57], v[56:57], v[214:215]
	v_pk_fma_f32 v[216:217], v[40:41], v[40:41], v[216:217]
	v_pk_fma_f32 v[218:219], v[24:25], v[24:25], v[218:219]
	v_pk_fma_f32 v[220:221], v[8:9], v[8:9], v[220:221]
	v_pk_fma_f32 v[206:207], v[114:115], v[114:115], v[206:207]
	v_pk_fma_f32 v[208:209], v[98:99], v[98:99], v[208:209]
	v_pk_fma_f32 v[210:211], v[82:83], v[82:83], v[210:211]
	v_pk_fma_f32 v[212:213], v[66:67], v[66:67], v[212:213]
	v_pk_fma_f32 v[214:215], v[50:51], v[50:51], v[214:215]
	v_pk_fma_f32 v[216:217], v[34:35], v[34:35], v[216:217]
	v_pk_fma_f32 v[218:219], v[18:19], v[18:19], v[218:219]
	v_pk_fma_f32 v[220:221], v[2:3], v[2:3], v[220:221]
	v_pk_fma_f32 v[206:207], v[116:117], v[116:117], v[206:207]
	v_pk_fma_f32 v[208:209], v[100:101], v[100:101], v[208:209]
	v_pk_fma_f32 v[210:211], v[84:85], v[84:85], v[210:211]
	v_pk_fma_f32 v[212:213], v[68:69], v[68:69], v[212:213]
	v_pk_fma_f32 v[214:215], v[52:53], v[52:53], v[214:215]
	v_pk_fma_f32 v[216:217], v[36:37], v[36:37], v[216:217]
	v_pk_fma_f32 v[218:219], v[20:21], v[20:21], v[218:219]
	v_pk_fma_f32 v[220:221], v[4:5], v[4:5], v[220:221]
	v_add_f32_e32 v178, v206, v207
	v_add_f32_e32 v179, v208, v209
	v_add_f32_e32 v180, v210, v211
	v_add_f32_e32 v181, v212, v213
	v_add_f32_e32 v182, v214, v215
	v_add_f32_e32 v183, v216, v217
	v_add_f32_e32 v184, v218, v219
	v_add_f32_e32 v185, v220, v221
	ds_swizzle_b32 v206, v178 offset:0x401f
	ds_swizzle_b32 v208, v179 offset:0x401f
	ds_swizzle_b32 v210, v180 offset:0x401f
	ds_swizzle_b32 v212, v181 offset:0x401f
	ds_swizzle_b32 v214, v182 offset:0x401f
	ds_swizzle_b32 v216, v183 offset:0x401f
	ds_swizzle_b32 v218, v184 offset:0x401f
	ds_swizzle_b32 v220, v185 offset:0x401f
	s_waitcnt lgkmcnt(0)
	v_add_f32_e32 v178, v178, v206
	v_add_f32_e32 v179, v179, v208
	v_add_f32_e32 v180, v180, v210
	v_add_f32_e32 v181, v181, v212
	v_add_f32_e32 v182, v182, v214
	v_add_f32_e32 v183, v183, v216
	v_add_f32_e32 v184, v184, v218
	v_add_f32_e32 v185, v185, v220
	v_mov_b32_e32 v206, v178
	v_mov_b32_e32 v208, v179
	v_mov_b32_e32 v210, v180
	v_mov_b32_e32 v212, v181
	v_mov_b32_e32 v214, v182
	v_mov_b32_e32 v216, v183
	v_mov_b32_e32 v218, v184
	v_mov_b32_e32 v220, v185
	v_permlane32_swap_b32_e32 v178, v206
	v_permlane32_swap_b32_e32 v179, v208
	v_permlane32_swap_b32_e32 v180, v210
	v_permlane32_swap_b32_e32 v181, v212
	v_permlane32_swap_b32_e32 v182, v214
	v_permlane32_swap_b32_e32 v183, v216
	v_permlane32_swap_b32_e32 v184, v218
	v_permlane32_swap_b32_e32 v185, v220
	v_add_f32_e32 v178, v178, v206
	v_add_f32_e32 v179, v179, v208
	v_add_f32_e32 v180, v180, v210
	v_add_f32_e32 v181, v181, v212
	v_add_f32_e32 v182, v182, v214
	v_add_f32_e32 v183, v183, v216
	v_add_f32_e32 v184, v184, v218
	v_add_f32_e32 v185, v185, v220
	v_fmamk_f32 v178, v178, 0x3c800000, v190
	v_fmamk_f32 v179, v179, 0x3c800000, v190
	v_fmamk_f32 v180, v180, 0x3c800000, v190
	v_fmamk_f32 v181, v181, 0x3c800000, v190
	v_fmamk_f32 v182, v182, 0x3c800000, v190
	v_fmamk_f32 v183, v183, 0x3c800000, v190
	v_fmamk_f32 v184, v184, 0x3c800000, v190
	v_fmamk_f32 v185, v185, 0x3c800000, v190
	v_rsq_f32_e32 v178, v178
	v_rsq_f32_e32 v179, v179
	v_rsq_f32_e32 v180, v180
	v_rsq_f32_e32 v181, v181
	v_rsq_f32_e32 v182, v182
	v_rsq_f32_e32 v183, v183
	v_rsq_f32_e32 v184, v184
	v_rsq_f32_e32 v185, v185
	v_mul_f32_e32 v178, s21, v178
	v_mul_f32_e32 v179, s21, v179
	v_mul_f32_e32 v180, s21, v180
	v_mul_f32_e32 v181, s21, v181
	v_mul_f32_e32 v182, s21, v182
	v_mul_f32_e32 v183, s21, v183
	v_mul_f32_e32 v184, s21, v184
	v_mul_f32_e32 v185, s21, v185
	global_load_dwordx4 v[206:209], v234, s[78:79] offset:0
	global_load_dwordx4 v[210:213], v234, s[78:79] offset:16
	global_load_dwordx4 v[214:217], v234, s[22:23] offset:0
	global_load_dwordx4 v[218:221], v234, s[22:23] offset:16
	s_waitcnt vmcnt(8)
	v_pk_mul_f32 v[126:127], v[126:127], v[178:179] op_sel_hi:[1,0]
	v_pk_mul_f32 v[128:129], v[128:129], v[178:179] op_sel_hi:[1,0]
	v_pk_mul_f32 v[122:123], v[122:123], v[178:179] op_sel_hi:[1,0]
	v_pk_mul_f32 v[124:125], v[124:125], v[178:179] op_sel_hi:[1,0]
	v_pk_mul_f32 v[118:119], v[118:119], v[178:179] op_sel_hi:[1,0]
	v_pk_mul_f32 v[120:121], v[120:121], v[178:179] op_sel_hi:[1,0]
	v_pk_mul_f32 v[114:115], v[114:115], v[178:179] op_sel_hi:[1,0]
	v_pk_mul_f32 v[116:117], v[116:117], v[178:179] op_sel_hi:[1,0]
	v_pk_mul_f32 v[126:127], v[126:127], v[142:143]
	v_pk_mul_f32 v[128:129], v[128:129], v[144:145]
	v_pk_mul_f32 v[122:123], v[122:123], v[138:139]
	v_pk_mul_f32 v[124:125], v[124:125], v[140:141]
	v_pk_mul_f32 v[118:119], v[118:119], v[134:135]
	v_pk_mul_f32 v[120:121], v[120:121], v[136:137]
	v_pk_mul_f32 v[114:115], v[114:115], v[130:131]
	v_pk_mul_f32 v[116:117], v[116:117], v[132:133]
	s_cmp_eq_u32 s20, 0
	s_cbranch_scc1 .Lwin_norope_0
	v_pk_mul_f32 v[192:193], v[118:119], v[154:155]
	v_pk_mul_f32 v[194:195], v[120:121], v[156:157]
	v_pk_mul_f32 v[118:119], v[118:119], v[146:147]
	v_pk_mul_f32 v[120:121], v[120:121], v[148:149]
	v_pk_fma_f32 v[118:119], v[126:127], v[154:155], v[118:119]
	v_pk_fma_f32 v[120:121], v[128:129], v[156:157], v[120:121]
	v_pk_fma_f32 v[126:127], v[126:127], v[146:147], v[192:193] neg_lo:[0,0,1] neg_hi:[0,0,1]
	v_pk_fma_f32 v[128:129], v[128:129], v[148:149], v[194:195] neg_lo:[0,0,1] neg_hi:[0,0,1]
	v_pk_mul_f32 v[192:193], v[114:115], v[158:159]
	v_pk_mul_f32 v[194:195], v[116:117], v[160:161]
	v_pk_mul_f32 v[114:115], v[114:115], v[150:151]
	v_pk_mul_f32 v[116:117], v[116:117], v[152:153]
	v_pk_fma_f32 v[114:115], v[122:123], v[158:159], v[114:115]
	v_pk_fma_f32 v[116:117], v[124:125], v[160:161], v[116:117]
	v_pk_fma_f32 v[122:123], v[122:123], v[150:151], v[192:193] neg_lo:[0,0,1] neg_hi:[0,0,1]
	v_pk_fma_f32 v[124:125], v[124:125], v[152:153], v[194:195] neg_lo:[0,0,1] neg_hi:[0,0,1]
